# rmsnorm row loops: norm weights hoisted out of the row loop into registers, eight row stores issued back to back, next row prefetched one iteration ahead (software pipeline)
# speedup vs baseline: 1.0521x; 1.0009x over previous
; __device__ __forceinline__ int opaque_tid() { int t = threadIdx.x; asm volatile("" : "+v"(t)); return t; }
; __device__ __forceinline__ void st_bf4(bf16_t* p, const f32x4 v) { u32x2 w; w.x = cvt_pk_bf16(v[0], v[1]); w.y = cvt_pk_bf16(v[2], v[3]); *(u32x2*)p = w; }
; template <bool F32OUT>
; __device__ __forceinline__ void rmsnorm_rows(const float* x, const float* w, bf16_t* outb, float* outf) {
;     const int tid_ = opaque_tid(); const int lane = tid_ & 63, gw = blockIdx.x * 8 + (tid_ >> 6), nw = gridDim.x * 8;
;     for (int row = gw; row < T_; row += nw) {
;         const float* xr = x + (size_t)row * D_; f32x4 v[8]; float ss = 0.f;
; #pragma unroll
;         for (int i = 0; i < 8; ++i) { v[i] = *(const f32x4*)(xr + i * 256 + lane * 4); ss += v[i][0] * v[i][0] + v[i][1] * v[i][1] + v[i][2] * v[i][2] + v[i][3] * v[i][3]; }
;         ss = wave_sum(ss);
;         const float rstd = 1.0f / sqrtf(ss * (1.0f / D_) + 1e-6f);
; #pragma unroll
;         for (int i = 0; i < 8; ++i) { const f32x4 wv = *(const f32x4*)(w + i * 256 + lane * 4); const f32x4 y = v[i] * rstd * wv;
;             if (F32OUT) *(f32x4*)(outf + (size_t)row * D_ + i * 256 + lane * 4) = y; else st_bf4(outb + (size_t)row * D_ + i * 256 + lane * 4, y); }
.LBB0_114:
	v_mov_b32_e32 v0, v192
	s_lshl_b32 s0, s2, 3
	v_ashrrev_i32_e32 v1, 6, v0
	v_writelane_b32 v248, s0, 22
	v_add_u32_e32 v16, s0, v1
	s_mov_b32 s0, 0x8000
	s_lshl_b32 s42, s68, 3
	v_cmp_gt_i32_e32 vcc, s0, v16
	v_mbcnt_lo_u32_b32 v193, -1, 0
	s_and_saveexec_b64 s[6:7], vcc
	s_cbranch_execz .LBB0_117
	v_mbcnt_hi_u32_b32 v1, -1, v193
	v_and_b32_e32 v2, 64, v1
	v_add_u32_e32 v2, 64, v2
	v_xor_b32_e32 v3, 32, v1
	v_cmp_lt_i32_e32 vcc, v3, v2
	v_ashrrev_i32_e32 v17, 31, v16
	v_and_b32_e32 v4, 63, v0
	v_cndmask_b32_e32 v3, v1, v3, vcc
	v_lshlrev_b32_e32 v32, 2, v3
	v_xor_b32_e32 v3, 16, v1
	v_cmp_lt_i32_e32 vcc, v3, v2
	s_mov_b64 s[0:1], 0x1000
	s_mov_b64 s[4:5], 0x1400
	v_cndmask_b32_e32 v3, v1, v3, vcc
	v_lshlrev_b32_e32 v33, 2, v3
	v_xor_b32_e32 v3, 8, v1
	v_cmp_lt_i32_e32 vcc, v3, v2
	s_ashr_i32 s43, s42, 31
	s_lshl_b64 s[8:9], s[42:43], 13
	v_cndmask_b32_e32 v3, v1, v3, vcc
	v_lshlrev_b32_e32 v34, 2, v3
	v_xor_b32_e32 v3, 4, v1
	v_cmp_lt_i32_e32 vcc, v3, v2
	s_lshl_b64 s[10:11], s[42:43], 12
	s_mov_b64 s[14:15], 0
	v_cndmask_b32_e32 v3, v1, v3, vcc
	v_lshlrev_b32_e32 v35, 2, v3
	v_xor_b32_e32 v3, 2, v1
	v_cmp_lt_i32_e32 vcc, v3, v2
	v_mov_b32_e32 v38, 0x260
	s_nop 0
	v_cndmask_b32_e32 v3, v1, v3, vcc
	v_lshlrev_b32_e32 v36, 2, v3
	v_xor_b32_e32 v3, 1, v1
	v_cmp_lt_i32_e32 vcc, v3, v2
	s_nop 1
	v_cndmask_b32_e32 v1, v1, v3, vcc
	v_lshlrev_b32_e32 v37, 2, v1
	v_lshlrev_b32_e32 v1, 4, v0
	v_and_b32_e32 v2, 0x3f0, v1
	v_mov_b32_e32 v3, 0
	v_lshl_add_u64 v[18:19], s[40:41], 0, v[2:3]
	v_lshlrev_b64 v[2:3], 13, v[16:17]
	v_lshl_or_b32 v2, v4, 4, v2
	v_lshl_add_u64 v[0:1], s[36:37], 0, v[2:3]
	v_lshl_add_u64 v[28:29], v[0:1], 0, s[0:1]
	v_lshlrev_b64 v[0:1], 12, v[16:17]
	v_lshl_add_u64 v[22:23], v[18:19], 0, s[4:5]
	s_mov_b64 s[4:5], 0x1800
	v_lshl_or_b32 v0, v4, 3, v0
	v_lshl_add_u64 v[20:21], v[18:19], 0, s[0:1]
	v_lshl_add_u64 v[24:25], v[18:19], 0, s[4:5]
	s_mov_b64 s[4:5], 0x1c00
	v_lshl_add_u64 v[0:1], s[30:31], 0, v[0:1]
	s_mov_b64 s[0:1], 0x15550800
	v_lshl_add_u64 v[26:27], v[18:19], 0, s[4:5]
	v_lshl_add_u64 v[30:31], v[0:1], 0, s[0:1]
	v_mov_b32_e32 v17, 0x358637bd
	s_mov_b32 s0, 0xf800000
	s_movk_i32 s1, 0x7fff
	global_load_dwordx4 v[100:103], v[18:19], off
	global_load_dwordx4 v[104:107], v[18:19], off offset:1024
	global_load_dwordx4 v[108:111], v[18:19], off offset:2048
	global_load_dwordx4 v[112:115], v[18:19], off offset:3072
	global_load_dwordx4 v[116:119], v[20:21], off
	global_load_dwordx4 v[120:123], v[22:23], off
	global_load_dwordx4 v[124:127], v[24:25], off
	global_load_dwordx4 v[128:131], v[26:27], off
	global_load_dwordx4 v[220:223], v[28:29], off offset:2048
	global_load_dwordx4 v[224:227], v[28:29], off offset:3072
	global_load_dwordx4 v[196:199], v[28:29], off offset:-4096
	global_load_dwordx4 v[200:203], v[28:29], off offset:-3072
	global_load_dwordx4 v[204:207], v[28:29], off offset:-2048
	global_load_dwordx4 v[208:211], v[28:29], off offset:-1024
	global_load_dwordx4 v[212:215], v[28:29], off
	global_load_dwordx4 v[216:219], v[28:29], off offset:1024
	v_add_u32_e32 v16, s42, v16
	v_lshl_add_u64 v[28:29], v[28:29], 0, s[8:9]
	s_waitcnt vmcnt(0)
.LBB0_116:
	s_waitcnt vmcnt(8)
	v_mov_b32_e32 v40, v196
	v_mov_b32_e32 v41, v197
	v_mov_b32_e32 v42, v198
	v_mov_b32_e32 v43, v199
	v_mov_b32_e32 v44, v200
	v_mov_b32_e32 v45, v201
	v_mov_b32_e32 v46, v202
	v_mov_b32_e32 v47, v203
	v_mov_b32_e32 v48, v204
	v_mov_b32_e32 v49, v205
	v_mov_b32_e32 v50, v206
	v_mov_b32_e32 v51, v207
	v_mov_b32_e32 v52, v208
	v_mov_b32_e32 v53, v209
	v_mov_b32_e32 v54, v210
	v_mov_b32_e32 v55, v211
	v_mov_b32_e32 v12, v212
	v_mov_b32_e32 v13, v213
	v_mov_b32_e32 v14, v214
	v_mov_b32_e32 v15, v215
	v_mov_b32_e32 v8, v216
	v_mov_b32_e32 v9, v217
	v_mov_b32_e32 v10, v218
	v_mov_b32_e32 v11, v219
	v_mov_b32_e32 v4, v220
	v_mov_b32_e32 v5, v221
	v_mov_b32_e32 v6, v222
	v_mov_b32_e32 v7, v223
	v_mov_b32_e32 v0, v224
	v_mov_b32_e32 v1, v225
	v_mov_b32_e32 v2, v226
	v_mov_b32_e32 v3, v227
	v_cmp_lt_i32_e32 vcc, s1, v16
	s_or_b64 s[14:15], vcc, s[14:15]
	s_mov_b64 s[86:87], exec
	s_andn2_b64 exec, exec, s[14:15]
	global_load_dwordx4 v[220:223], v[28:29], off offset:2048
	global_load_dwordx4 v[224:227], v[28:29], off offset:3072
	global_load_dwordx4 v[196:199], v[28:29], off offset:-4096
	global_load_dwordx4 v[200:203], v[28:29], off offset:-3072
	global_load_dwordx4 v[204:207], v[28:29], off offset:-2048
	global_load_dwordx4 v[208:211], v[28:29], off offset:-1024
	global_load_dwordx4 v[212:215], v[28:29], off
	global_load_dwordx4 v[216:219], v[28:29], off offset:1024
	s_mov_b64 exec, s[86:87]
	v_add_u32_e32 v16, s42, v16
	v_lshl_add_u64 v[28:29], v[28:29], 0, s[8:9]
	v_mov_b32_e32 v62, v5
	v_mov_b32_e32 v63, v1
	v_mul_f32_e32 v39, v41, v41
	v_mul_f32_e32 v68, v45, v45
	v_mul_f32_e32 v69, v49, v49
	v_fmac_f32_e32 v39, v40, v40
	v_fmac_f32_e32 v68, v44, v44
	v_mul_f32_e32 v70, v53, v53
	v_fmac_f32_e32 v69, v48, v48
	v_fmac_f32_e32 v39, v42, v42
	v_fmac_f32_e32 v68, v46, v46
	v_mul_f32_e32 v71, v13, v13
	v_fmac_f32_e32 v70, v52, v52
	v_fmac_f32_e32 v69, v50, v50
	v_fmac_f32_e32 v39, v43, v43
	v_fmac_f32_e32 v68, v47, v47
	v_mul_f32_e32 v72, v9, v9
	v_fmac_f32_e32 v71, v12, v12
	v_fmac_f32_e32 v70, v54, v54
	v_fmac_f32_e32 v69, v51, v51
	v_add_f32_e32 v39, v39, v68
	v_mov_b32_e32 v60, v4
	v_mov_b32_e32 v61, v0
	v_pk_mul_f32 v[62:63], v[62:63], v[62:63]
	v_fmac_f32_e32 v72, v8, v8
	v_fmac_f32_e32 v71, v14, v14
	v_fmac_f32_e32 v70, v55, v55
	v_add_f32_e32 v39, v39, v69
	v_mov_b32_e32 v64, v6
	v_mov_b32_e32 v65, v2
	v_pk_fma_f32 v[60:61], v[60:61], v[60:61], v[62:63]
	v_fmac_f32_e32 v72, v10, v10
	v_fmac_f32_e32 v71, v15, v15
	v_add_f32_e32 v39, v39, v70
	v_mov_b32_e32 v66, v7
	v_mov_b32_e32 v67, v3
	v_pk_fma_f32 v[60:61], v[64:65], v[64:65], v[60:61]
	v_fmac_f32_e32 v72, v11, v11
	v_add_f32_e32 v39, v39, v71
	v_pk_fma_f32 v[60:61], v[66:67], v[66:67], v[60:61]
	v_add_f32_e32 v39, v39, v72
	v_add_f32_e32 v39, v39, v60
	v_add_f32_e32 v39, v39, v61
	ds_bpermute_b32 v60, v32, v39
	s_waitcnt lgkmcnt(0)
; __device__ __forceinline__ int opaque_tid() { int t = threadIdx.x; asm volatile("" : "+v"(t)); return t; }
; __device__ __forceinline__ void st_bf4(bf16_t* p, const f32x4 v) { u32x2 w; w.x = cvt_pk_bf16(v[0], v[1]); w.y = cvt_pk_bf16(v[2], v[3]); *(u32x2*)p = w; }
; __device__ __forceinline__ float wave_sum(float v) {
; #pragma unroll
;     for (int o = 32; o >= 1; o >>= 1) v += __shfl_xor(v, o);
;     return v;
; }
; template <bool F32OUT>
; __device__ __forceinline__ void rmsnorm_rows(const float* x, const float* w, bf16_t* outb, float* outf) {
;     const int tid_ = opaque_tid(); const int lane = tid_ & 63, gw = blockIdx.x * 8 + (tid_ >> 6), nw = gridDim.x * 8;
;     for (int row = gw; row < T_; row += nw) {
;         const float* xr = x + (size_t)row * D_; f32x4 v[8]; float ss = 0.f;
; #pragma unroll
;         for (int i = 0; i < 8; ++i) { v[i] = *(const f32x4*)(xr + i * 256 + lane * 4); ss += v[i][0] * v[i][0] + v[i][1] * v[i][1] + v[i][2] * v[i][2] + v[i][3] * v[i][3]; }
;         ss = wave_sum(ss);
;         const float rstd = 1.0f / sqrtf(ss * (1.0f / D_) + 1e-6f);
; #pragma unroll
;         for (int i = 0; i < 8; ++i) { const f32x4 wv = *(const f32x4*)(w + i * 256 + lane * 4); const f32x4 y = v[i] * rstd * wv;
;             if (F32OUT) *(f32x4*)(outf + (size_t)row * D_ + i * 256 + lane * 4) = y; else st_bf4(outb + (size_t)row * D_ + i * 256 + lane * 4, y); }
	v_add_f32_e32 v39, v39, v60
	ds_bpermute_b32 v60, v33, v39
	s_waitcnt lgkmcnt(0)
	v_add_f32_e32 v39, v39, v60
	ds_bpermute_b32 v60, v34, v39
	s_waitcnt lgkmcnt(0)
	v_add_f32_e32 v39, v39, v60
	ds_bpermute_b32 v60, v35, v39
	s_waitcnt lgkmcnt(0)
	v_add_f32_e32 v39, v39, v60
	ds_bpermute_b32 v60, v36, v39
	s_waitcnt lgkmcnt(0)
	v_add_f32_e32 v39, v39, v60
	ds_bpermute_b32 v60, v37, v39
	s_waitcnt lgkmcnt(0)
	v_add_f32_e32 v39, v39, v60
	v_fmamk_f32 v39, v39, 0x3a000000, v17
	v_mul_f32_e32 v60, 0x4f800000, v39
	v_cmp_gt_f32_e32 vcc, s0, v39
	s_nop 1
	v_cndmask_b32_e32 v39, v39, v60, vcc
	v_sqrt_f32_e32 v60, v39
	s_nop 0
	v_add_u32_e32 v61, -1, v60
	v_add_u32_e32 v62, 1, v60
	v_fma_f32 v63, -v61, v60, v39
	v_fma_f32 v64, -v62, v60, v39
	v_cmp_ge_f32_e64 s[4:5], 0, v63
	s_nop 1
	v_cndmask_b32_e64 v60, v60, v61, s[4:5]
	v_cmp_lt_f32_e64 s[4:5], 0, v64
	s_nop 1
	v_cndmask_b32_e64 v60, v60, v62, s[4:5]
	v_mul_f32_e32 v61, 0x37800000, v60
	v_cndmask_b32_e32 v60, v60, v61, vcc
	v_cmp_class_f32_e32 vcc, v39, v38
	s_nop 1
	v_cndmask_b32_e32 v39, v60, v39, vcc
	v_div_scale_f32 v60, s[4:5], v39, v39, 1.0
	v_rcp_f32_e32 v62, v60
	v_div_scale_f32 v61, vcc, 1.0, v39, 1.0
	v_fma_f32 v63, -v60, v62, 1.0
	v_fmac_f32_e32 v62, v63, v62
	v_mul_f32_e32 v63, v61, v62
	v_fma_f32 v64, -v60, v63, v61
	v_fmac_f32_e32 v63, v64, v62
	v_fma_f32 v60, -v60, v63, v61
	v_div_fmas_f32 v60, v60, v62, v63
	v_div_fixup_f32 v60, v60, v39, 1.0
	v_pk_mul_f32 v[40:41], v[40:41], v[60:61] op_sel_hi:[1,0]
	v_pk_mul_f32 v[42:43], v[42:43], v[60:61] op_sel_hi:[1,0]
	v_pk_mul_f32 v[40:41], v[100:101], v[40:41]
	v_pk_mul_f32 v[42:43], v[102:103], v[42:43]
	v_cvt_pk_bf16_f32 v40, v40, v41
	s_nop 0
	v_cvt_pk_bf16_f32 v41, v42, v43
	global_store_dwordx2 v[30:31], v[40:41], off
	v_pk_mul_f32 v[44:45], v[44:45], v[60:61] op_sel_hi:[1,0]
	v_pk_mul_f32 v[46:47], v[46:47], v[60:61] op_sel_hi:[1,0]
	v_pk_mul_f32 v[44:45], v[104:105], v[44:45]
	v_pk_mul_f32 v[46:47], v[106:107], v[46:47]
	v_cvt_pk_bf16_f32 v44, v44, v45
	s_nop 0
	v_cvt_pk_bf16_f32 v45, v46, v47
	global_store_dwordx2 v[30:31], v[44:45], off offset:512
	v_pk_mul_f32 v[48:49], v[48:49], v[60:61] op_sel_hi:[1,0]
	v_pk_mul_f32 v[50:51], v[50:51], v[60:61] op_sel_hi:[1,0]
	v_pk_mul_f32 v[48:49], v[108:109], v[48:49]
	v_pk_mul_f32 v[50:51], v[110:111], v[50:51]
	v_cvt_pk_bf16_f32 v48, v48, v49
	s_nop 0
	v_cvt_pk_bf16_f32 v49, v50, v51
	global_store_dwordx2 v[30:31], v[48:49], off offset:1024
	v_pk_mul_f32 v[52:53], v[52:53], v[60:61] op_sel_hi:[1,0]
	v_pk_mul_f32 v[54:55], v[54:55], v[60:61] op_sel_hi:[1,0]
	v_pk_mul_f32 v[52:53], v[112:113], v[52:53]
	v_pk_mul_f32 v[54:55], v[114:115], v[54:55]
	v_cvt_pk_bf16_f32 v52, v52, v53
	s_nop 0
	v_cvt_pk_bf16_f32 v53, v54, v55
	global_store_dwordx2 v[30:31], v[52:53], off offset:1536
	v_pk_mul_f32 v[12:13], v[12:13], v[60:61] op_sel_hi:[1,0]
	v_pk_mul_f32 v[14:15], v[14:15], v[60:61] op_sel_hi:[1,0]
	v_pk_mul_f32 v[12:13], v[116:117], v[12:13]
	v_pk_mul_f32 v[14:15], v[118:119], v[14:15]
	v_cvt_pk_bf16_f32 v12, v12, v13
	s_nop 0
	v_cvt_pk_bf16_f32 v13, v14, v15
	global_store_dwordx2 v[30:31], v[12:13], off offset:2048
	v_pk_mul_f32 v[8:9], v[8:9], v[60:61] op_sel_hi:[1,0]
	v_pk_mul_f32 v[10:11], v[10:11], v[60:61] op_sel_hi:[1,0]
	v_pk_mul_f32 v[8:9], v[120:121], v[8:9]
	v_pk_mul_f32 v[10:11], v[122:123], v[10:11]
	v_cvt_pk_bf16_f32 v8, v8, v9
	s_nop 0
	v_cvt_pk_bf16_f32 v9, v10, v11
	global_store_dwordx2 v[30:31], v[8:9], off offset:2560
	v_pk_mul_f32 v[4:5], v[4:5], v[60:61] op_sel_hi:[1,0]
	v_pk_mul_f32 v[6:7], v[6:7], v[60:61] op_sel_hi:[1,0]
	v_pk_mul_f32 v[4:5], v[124:125], v[4:5]
	v_pk_mul_f32 v[6:7], v[126:127], v[6:7]
	v_cvt_pk_bf16_f32 v4, v4, v5
	s_nop 0
	v_cvt_pk_bf16_f32 v5, v6, v7
	global_store_dwordx2 v[30:31], v[4:5], off offset:3072
	v_pk_mul_f32 v[0:1], v[0:1], v[60:61] op_sel_hi:[1,0]
	v_pk_mul_f32 v[2:3], v[2:3], v[60:61] op_sel_hi:[1,0]
	v_pk_mul_f32 v[0:1], v[128:129], v[0:1]
	v_pk_mul_f32 v[2:3], v[130:131], v[2:3]
	v_cvt_pk_bf16_f32 v0, v0, v1
	s_nop 0
	v_cvt_pk_bf16_f32 v1, v2, v3
	global_store_dwordx2 v[30:31], v[0:1], off offset:3584
	v_lshl_add_u64 v[30:31], v[30:31], 0, s[10:11]
	s_andn2_b64 exec, exec, s[14:15]
	s_cbranch_execnz .LBB0_116

; __device__ __forceinline__ int opaque_tid() { int t = threadIdx.x; asm volatile("" : "+v"(t)); return t; }
; __device__ __forceinline__ void st_bf4(bf16_t* p, const f32x4 v) { u32x2 w; w.x = cvt_pk_bf16(v[0], v[1]); w.y = cvt_pk_bf16(v[2], v[3]); *(u32x2*)p = w; }
; template <bool F32OUT>
; __device__ __forceinline__ void rmsnorm_rows(const float* x, const float* w, bf16_t* outb, float* outf) {
;     const int tid_ = opaque_tid(); const int lane = tid_ & 63, gw = blockIdx.x * 8 + (tid_ >> 6), nw = gridDim.x * 8;
;     for (int row = gw; row < T_; row += nw) {
;         const float* xr = x + (size_t)row * D_; f32x4 v[8]; float ss = 0.f;
; #pragma unroll
;         for (int i = 0; i < 8; ++i) { v[i] = *(const f32x4*)(xr + i * 256 + lane * 4); ss += v[i][0] * v[i][0] + v[i][1] * v[i][1] + v[i][2] * v[i][2] + v[i][3] * v[i][3]; }
;         ss = wave_sum(ss);
;         const float rstd = 1.0f / sqrtf(ss * (1.0f / D_) + 1e-6f);
; #pragma unroll
;         for (int i = 0; i < 8; ++i) { const f32x4 wv = *(const f32x4*)(w + i * 256 + lane * 4); const f32x4 y = v[i] * rstd * wv;
;             if (F32OUT) *(f32x4*)(outf + (size_t)row * D_ + i * 256 + lane * 4) = y; else st_bf4(outb + (size_t)row * D_ + i * 256 + lane * 4, y); }
.LBB0_313:
	s_or_b64 exec, exec, s[4:5]
	s_waitcnt lgkmcnt(0)
	v_mov_b32_e32 v0, v192
	s_barrier
	v_readlane_b32 s0, v248, 22
	v_ashrrev_i32_e32 v1, 6, v0
	s_nop 0
	v_add_u32_e32 v12, s0, v1
	s_mov_b32 s0, 0x8000
	v_cmp_gt_i32_e32 vcc, s0, v12
	s_and_saveexec_b64 s[6:7], vcc
	s_cbranch_execz .LBB0_316
	v_mbcnt_hi_u32_b32 v1, -1, v193
	v_and_b32_e32 v2, 64, v1
	v_add_u32_e32 v2, 64, v2
	v_xor_b32_e32 v3, 32, v1
	v_cmp_lt_i32_e32 vcc, v3, v2
	v_ashrrev_i32_e32 v13, 31, v12
	v_and_b32_e32 v4, 63, v0
	v_cndmask_b32_e32 v3, v1, v3, vcc
	v_lshlrev_b32_e32 v28, 2, v3
	v_xor_b32_e32 v3, 16, v1
	v_cmp_lt_i32_e32 vcc, v3, v2
	s_mov_b64 s[0:1], 0x1000
	s_mov_b64 s[4:5], 0x1400
	v_cndmask_b32_e32 v3, v1, v3, vcc
	v_lshlrev_b32_e32 v29, 2, v3
	v_xor_b32_e32 v3, 8, v1
	v_cmp_lt_i32_e32 vcc, v3, v2
	s_ashr_i32 s43, s42, 31
	s_lshl_b64 s[8:9], s[42:43], 13
	v_cndmask_b32_e32 v3, v1, v3, vcc
	v_lshlrev_b32_e32 v30, 2, v3
	v_xor_b32_e32 v3, 4, v1
	v_cmp_lt_i32_e32 vcc, v3, v2
	s_lshl_b64 s[10:11], s[42:43], 12
	s_mov_b64 s[14:15], 0
	v_cndmask_b32_e32 v3, v1, v3, vcc
	v_lshlrev_b32_e32 v31, 2, v3
	v_xor_b32_e32 v3, 2, v1
	v_cmp_lt_i32_e32 vcc, v3, v2
	v_mov_b32_e32 v34, 0x260
	s_nop 0
	v_cndmask_b32_e32 v3, v1, v3, vcc
	v_lshlrev_b32_e32 v32, 2, v3
	v_xor_b32_e32 v3, 1, v1
	v_cmp_lt_i32_e32 vcc, v3, v2
	s_nop 1
	v_cndmask_b32_e32 v1, v1, v3, vcc
	v_lshlrev_b32_e32 v33, 2, v1
	v_lshlrev_b32_e32 v1, 4, v0
	v_and_b32_e32 v2, 0x3f0, v1
	v_mov_b32_e32 v3, 0
	v_lshl_add_u64 v[14:15], s[46:47], 0, v[2:3]
	v_lshlrev_b64 v[2:3], 13, v[12:13]
	v_lshl_or_b32 v2, v4, 4, v2
	v_lshl_add_u64 v[0:1], s[28:29], 0, v[2:3]
	v_lshl_add_u64 v[24:25], v[0:1], 0, s[0:1]
	v_lshlrev_b64 v[0:1], 12, v[12:13]
	v_lshl_add_u64 v[18:19], v[14:15], 0, s[4:5]
	s_mov_b64 s[4:5], 0x1800
	v_lshl_or_b32 v0, v4, 3, v0
	v_lshl_add_u64 v[16:17], v[14:15], 0, s[0:1]
	v_lshl_add_u64 v[20:21], v[14:15], 0, s[4:5]
	s_mov_b64 s[4:5], 0x1c00
	v_lshl_add_u64 v[0:1], s[30:31], 0, v[0:1]
	s_mov_b64 s[0:1], 0x15550800
	v_lshl_add_u64 v[22:23], v[14:15], 0, s[4:5]
	v_lshl_add_u64 v[26:27], v[0:1], 0, s[0:1]
	v_mov_b32_e32 v13, 0x358637bd
	s_mov_b32 s0, 0xf800000
	s_movk_i32 s1, 0x7fff
	global_load_dwordx4 v[100:103], v[14:15], off
	global_load_dwordx4 v[104:107], v[14:15], off offset:1024
	global_load_dwordx4 v[108:111], v[14:15], off offset:2048
	global_load_dwordx4 v[112:115], v[14:15], off offset:3072
	global_load_dwordx4 v[116:119], v[16:17], off
	global_load_dwordx4 v[120:123], v[18:19], off
	global_load_dwordx4 v[124:127], v[20:21], off
	global_load_dwordx4 v[128:131], v[22:23], off
	global_load_dwordx4 v[196:199], v[24:25], off offset:-4096
	global_load_dwordx4 v[200:203], v[24:25], off offset:-3072
	global_load_dwordx4 v[204:207], v[24:25], off offset:-2048
	global_load_dwordx4 v[208:211], v[24:25], off offset:-1024
	global_load_dwordx4 v[212:215], v[24:25], off
	global_load_dwordx4 v[216:219], v[24:25], off offset:1024
	global_load_dwordx4 v[220:223], v[24:25], off offset:2048
	global_load_dwordx4 v[224:227], v[24:25], off offset:3072
	v_add_u32_e32 v12, s42, v12
	v_lshl_add_u64 v[24:25], v[24:25], 0, s[8:9]
	s_waitcnt vmcnt(0)
.LBB0_315:
	s_waitcnt vmcnt(8)
	v_mov_b32_e32 v36, v196
	v_mov_b32_e32 v37, v197
	v_mov_b32_e32 v38, v198
	v_mov_b32_e32 v39, v199
	v_mov_b32_e32 v40, v200
	v_mov_b32_e32 v41, v201
	v_mov_b32_e32 v42, v202
	v_mov_b32_e32 v43, v203
	v_mov_b32_e32 v44, v204
	v_mov_b32_e32 v45, v205
	v_mov_b32_e32 v46, v206
	v_mov_b32_e32 v47, v207
	v_mov_b32_e32 v48, v208
	v_mov_b32_e32 v49, v209
	v_mov_b32_e32 v50, v210
	v_mov_b32_e32 v51, v211
	v_mov_b32_e32 v52, v212
	v_mov_b32_e32 v53, v213
	v_mov_b32_e32 v54, v214
	v_mov_b32_e32 v55, v215
	v_mov_b32_e32 v8, v216
	v_mov_b32_e32 v9, v217
	v_mov_b32_e32 v10, v218
	v_mov_b32_e32 v11, v219
	v_mov_b32_e32 v4, v220
	v_mov_b32_e32 v5, v221
	v_mov_b32_e32 v6, v222
	v_mov_b32_e32 v7, v223
	v_mov_b32_e32 v0, v224
	v_mov_b32_e32 v1, v225
	v_mov_b32_e32 v2, v226
	v_mov_b32_e32 v3, v227
	v_cmp_lt_i32_e32 vcc, s1, v12
	s_or_b64 s[14:15], vcc, s[14:15]
	s_mov_b64 s[86:87], exec
	s_andn2_b64 exec, exec, s[14:15]
	global_load_dwordx4 v[196:199], v[24:25], off offset:-4096
	global_load_dwordx4 v[200:203], v[24:25], off offset:-3072
	global_load_dwordx4 v[204:207], v[24:25], off offset:-2048
	global_load_dwordx4 v[208:211], v[24:25], off offset:-1024
	global_load_dwordx4 v[212:215], v[24:25], off
	global_load_dwordx4 v[216:219], v[24:25], off offset:1024
	global_load_dwordx4 v[220:223], v[24:25], off offset:2048
	global_load_dwordx4 v[224:227], v[24:25], off offset:3072
	s_mov_b64 exec, s[86:87]
	v_add_u32_e32 v12, s42, v12
	v_lshl_add_u64 v[24:25], v[24:25], 0, s[8:9]
	v_mul_f32_e32 v35, v37, v37
	v_mul_f32_e32 v68, v41, v41
	v_mul_f32_e32 v69, v45, v45
	v_fmac_f32_e32 v35, v36, v36
	v_fmac_f32_e32 v68, v40, v40
	v_mul_f32_e32 v70, v49, v49
	v_fmac_f32_e32 v69, v44, v44
	v_fmac_f32_e32 v35, v38, v38
	v_fmac_f32_e32 v68, v42, v42
	v_mul_f32_e32 v71, v53, v53
	v_fmac_f32_e32 v70, v48, v48
	v_fmac_f32_e32 v69, v46, v46
	v_fmac_f32_e32 v35, v39, v39
	v_fmac_f32_e32 v68, v43, v43
	v_mul_f32_e32 v72, v9, v9
	v_mov_b32_e32 v62, v5
	v_mov_b32_e32 v63, v1
	v_fmac_f32_e32 v71, v52, v52
	v_fmac_f32_e32 v70, v50, v50
	v_fmac_f32_e32 v69, v47, v47
	v_add_f32_e32 v35, v35, v68
	v_mov_b32_e32 v60, v4
	v_mov_b32_e32 v61, v0
	v_fmac_f32_e32 v72, v8, v8
	v_pk_mul_f32 v[62:63], v[62:63], v[62:63]
	v_fmac_f32_e32 v71, v54, v54
	v_fmac_f32_e32 v70, v51, v51
	v_add_f32_e32 v35, v35, v69
	v_mov_b32_e32 v64, v6
	v_mov_b32_e32 v65, v2
	v_fmac_f32_e32 v72, v10, v10
	v_pk_fma_f32 v[60:61], v[60:61], v[60:61], v[62:63]
	v_fmac_f32_e32 v71, v55, v55
	v_add_f32_e32 v35, v35, v70
	v_mov_b32_e32 v66, v7
	v_mov_b32_e32 v67, v3
	v_fmac_f32_e32 v72, v11, v11
	v_pk_fma_f32 v[60:61], v[64:65], v[64:65], v[60:61]
	v_add_f32_e32 v35, v35, v71
	v_pk_fma_f32 v[60:61], v[66:67], v[66:67], v[60:61]
	v_add_f32_e32 v35, v35, v72
	v_add_f32_e32 v35, v35, v60
	v_add_f32_e32 v35, v35, v61
	ds_bpermute_b32 v60, v28, v35
	s_waitcnt lgkmcnt(0)
; __device__ __forceinline__ int opaque_tid() { int t = threadIdx.x; asm volatile("" : "+v"(t)); return t; }
; __device__ __forceinline__ void st_bf4(bf16_t* p, const f32x4 v) { u32x2 w; w.x = cvt_pk_bf16(v[0], v[1]); w.y = cvt_pk_bf16(v[2], v[3]); *(u32x2*)p = w; }
; __device__ __forceinline__ float wave_sum(float v) {
; #pragma unroll
;     for (int o = 32; o >= 1; o >>= 1) v += __shfl_xor(v, o);
;     return v;
; }
; template <bool F32OUT>
; __device__ __forceinline__ void rmsnorm_rows(const float* x, const float* w, bf16_t* outb, float* outf) {
;     const int tid_ = opaque_tid(); const int lane = tid_ & 63, gw = blockIdx.x * 8 + (tid_ >> 6), nw = gridDim.x * 8;
;     for (int row = gw; row < T_; row += nw) {
;         const float* xr = x + (size_t)row * D_; f32x4 v[8]; float ss = 0.f;
; #pragma unroll
;         for (int i = 0; i < 8; ++i) { v[i] = *(const f32x4*)(xr + i * 256 + lane * 4); ss += v[i][0] * v[i][0] + v[i][1] * v[i][1] + v[i][2] * v[i][2] + v[i][3] * v[i][3]; }
;         ss = wave_sum(ss);
;         const float rstd = 1.0f / sqrtf(ss * (1.0f / D_) + 1e-6f);
; #pragma unroll
;         for (int i = 0; i < 8; ++i) { const f32x4 wv = *(const f32x4*)(w + i * 256 + lane * 4); const f32x4 y = v[i] * rstd * wv;
;             if (F32OUT) *(f32x4*)(outf + (size_t)row * D_ + i * 256 + lane * 4) = y; else st_bf4(outb + (size_t)row * D_ + i * 256 + lane * 4, y); }
;     }
; }
	v_add_f32_e32 v35, v35, v60
	ds_bpermute_b32 v60, v29, v35
	s_waitcnt lgkmcnt(0)
	v_add_f32_e32 v35, v35, v60
	ds_bpermute_b32 v60, v30, v35
	s_waitcnt lgkmcnt(0)
	v_add_f32_e32 v35, v35, v60
	ds_bpermute_b32 v60, v31, v35
	s_waitcnt lgkmcnt(0)
	v_add_f32_e32 v35, v35, v60
	ds_bpermute_b32 v60, v32, v35
	s_waitcnt lgkmcnt(0)
	v_add_f32_e32 v35, v35, v60
	ds_bpermute_b32 v60, v33, v35
	s_waitcnt lgkmcnt(0)
	v_add_f32_e32 v35, v35, v60
	v_fmamk_f32 v35, v35, 0x3a000000, v13
	v_mul_f32_e32 v60, 0x4f800000, v35
	v_cmp_gt_f32_e32 vcc, s0, v35
	s_nop 1
	v_cndmask_b32_e32 v35, v35, v60, vcc
	v_sqrt_f32_e32 v60, v35
	s_nop 0
	v_add_u32_e32 v61, -1, v60
	v_add_u32_e32 v62, 1, v60
	v_fma_f32 v63, -v61, v60, v35
	v_fma_f32 v64, -v62, v60, v35
	v_cmp_ge_f32_e64 s[4:5], 0, v63
	s_nop 1
	v_cndmask_b32_e64 v60, v60, v61, s[4:5]
	v_cmp_lt_f32_e64 s[4:5], 0, v64
	s_nop 1
	v_cndmask_b32_e64 v60, v60, v62, s[4:5]
	v_mul_f32_e32 v61, 0x37800000, v60
	v_cndmask_b32_e32 v60, v60, v61, vcc
	v_cmp_class_f32_e32 vcc, v35, v34
	s_nop 1
	v_cndmask_b32_e32 v35, v60, v35, vcc
	v_div_scale_f32 v60, s[4:5], v35, v35, 1.0
	v_rcp_f32_e32 v62, v60
	v_div_scale_f32 v61, vcc, 1.0, v35, 1.0
	v_fma_f32 v63, -v60, v62, 1.0
	v_fmac_f32_e32 v62, v63, v62
	v_mul_f32_e32 v63, v61, v62
	v_fma_f32 v64, -v60, v63, v61
	v_fmac_f32_e32 v63, v64, v62
	v_fma_f32 v60, -v60, v63, v61
	v_div_fmas_f32 v60, v60, v62, v63
	v_div_fixup_f32 v60, v60, v35, 1.0
	v_pk_mul_f32 v[36:37], v[36:37], v[60:61] op_sel_hi:[1,0]
	v_pk_mul_f32 v[38:39], v[38:39], v[60:61] op_sel_hi:[1,0]
	v_pk_mul_f32 v[36:37], v[100:101], v[36:37]
	v_pk_mul_f32 v[38:39], v[102:103], v[38:39]
	v_cvt_pk_bf16_f32 v36, v36, v37
	s_nop 0
	v_cvt_pk_bf16_f32 v37, v38, v39
	global_store_dwordx2 v[26:27], v[36:37], off
	v_pk_mul_f32 v[40:41], v[40:41], v[60:61] op_sel_hi:[1,0]
	v_pk_mul_f32 v[42:43], v[42:43], v[60:61] op_sel_hi:[1,0]
	v_pk_mul_f32 v[40:41], v[104:105], v[40:41]
	v_pk_mul_f32 v[42:43], v[106:107], v[42:43]
	v_cvt_pk_bf16_f32 v40, v40, v41
	s_nop 0
	v_cvt_pk_bf16_f32 v41, v42, v43
	global_store_dwordx2 v[26:27], v[40:41], off offset:512
	v_pk_mul_f32 v[44:45], v[44:45], v[60:61] op_sel_hi:[1,0]
	v_pk_mul_f32 v[46:47], v[46:47], v[60:61] op_sel_hi:[1,0]
	v_pk_mul_f32 v[44:45], v[108:109], v[44:45]
	v_pk_mul_f32 v[46:47], v[110:111], v[46:47]
	v_cvt_pk_bf16_f32 v44, v44, v45
	s_nop 0
	v_cvt_pk_bf16_f32 v45, v46, v47
	global_store_dwordx2 v[26:27], v[44:45], off offset:1024
	v_pk_mul_f32 v[48:49], v[48:49], v[60:61] op_sel_hi:[1,0]
	v_pk_mul_f32 v[50:51], v[50:51], v[60:61] op_sel_hi:[1,0]
	v_pk_mul_f32 v[48:49], v[112:113], v[48:49]
	v_pk_mul_f32 v[50:51], v[114:115], v[50:51]
	v_cvt_pk_bf16_f32 v48, v48, v49
	s_nop 0
	v_cvt_pk_bf16_f32 v49, v50, v51
	global_store_dwordx2 v[26:27], v[48:49], off offset:1536
	v_pk_mul_f32 v[52:53], v[52:53], v[60:61] op_sel_hi:[1,0]
	v_pk_mul_f32 v[54:55], v[54:55], v[60:61] op_sel_hi:[1,0]
	v_pk_mul_f32 v[52:53], v[116:117], v[52:53]
	v_pk_mul_f32 v[54:55], v[118:119], v[54:55]
	v_cvt_pk_bf16_f32 v52, v52, v53
	s_nop 0
	v_cvt_pk_bf16_f32 v53, v54, v55
	global_store_dwordx2 v[26:27], v[52:53], off offset:2048
	v_pk_mul_f32 v[8:9], v[8:9], v[60:61] op_sel_hi:[1,0]
	v_pk_mul_f32 v[10:11], v[10:11], v[60:61] op_sel_hi:[1,0]
	v_pk_mul_f32 v[8:9], v[120:121], v[8:9]
	v_pk_mul_f32 v[10:11], v[122:123], v[10:11]
	v_cvt_pk_bf16_f32 v8, v8, v9
	s_nop 0
	v_cvt_pk_bf16_f32 v9, v10, v11
	global_store_dwordx2 v[26:27], v[8:9], off offset:2560
	v_pk_mul_f32 v[4:5], v[4:5], v[60:61] op_sel_hi:[1,0]
	v_pk_mul_f32 v[6:7], v[6:7], v[60:61] op_sel_hi:[1,0]
	v_pk_mul_f32 v[4:5], v[124:125], v[4:5]
	v_pk_mul_f32 v[6:7], v[126:127], v[6:7]
	v_cvt_pk_bf16_f32 v4, v4, v5
	s_nop 0
	v_cvt_pk_bf16_f32 v5, v6, v7
	global_store_dwordx2 v[26:27], v[4:5], off offset:3072
	v_pk_mul_f32 v[0:1], v[0:1], v[60:61] op_sel_hi:[1,0]
	v_pk_mul_f32 v[2:3], v[2:3], v[60:61] op_sel_hi:[1,0]
	v_pk_mul_f32 v[0:1], v[128:129], v[0:1]
	v_pk_mul_f32 v[2:3], v[130:131], v[2:3]
	v_cvt_pk_bf16_f32 v0, v0, v1
	s_nop 0
	v_cvt_pk_bf16_f32 v1, v2, v3
	global_store_dwordx2 v[26:27], v[0:1], off offset:3584
	v_lshl_add_u64 v[26:27], v[26:27], 0, s[10:11]
	s_andn2_b64 exec, exec, s[14:15]
	s_cbranch_execnz .LBB0_315

; __device__ __forceinline__ int opaque_tid() { int t = threadIdx.x; asm volatile("" : "+v"(t)); return t; }
; __device__ __forceinline__ void st_bf4(bf16_t* p, const f32x4 v) { u32x2 w; w.x = cvt_pk_bf16(v[0], v[1]); w.y = cvt_pk_bf16(v[2], v[3]); *(u32x2*)p = w; }
; __device__ __forceinline__ float wave_sum(float v) {
; #pragma unroll
;     for (int o = 32; o >= 1; o >>= 1) v += __shfl_xor(v, o);
;     return v;
; }
; template <bool F32OUT>
; __device__ __forceinline__ void rmsnorm_rows(const float* x, const float* w, bf16_t* outb, float* outf) {
;     const int tid_ = opaque_tid(); const int lane = tid_ & 63, gw = blockIdx.x * 8 + (tid_ >> 6), nw = gridDim.x * 8;
;     for (int row = gw; row < T_; row += nw) {
;         const float* xr = x + (size_t)row * D_; f32x4 v[8]; float ss = 0.f;
; #pragma unroll
;         for (int i = 0; i < 8; ++i) { v[i] = *(const f32x4*)(xr + i * 256 + lane * 4); ss += v[i][0] * v[i][0] + v[i][1] * v[i][1] + v[i][2] * v[i][2] + v[i][3] * v[i][3]; }
;         ss = wave_sum(ss);
;         const float rstd = 1.0f / sqrtf(ss * (1.0f / D_) + 1e-6f);
; #pragma unroll
;         for (int i = 0; i < 8; ++i) { const f32x4 wv = *(const f32x4*)(w + i * 256 + lane * 4); const f32x4 y = v[i] * rstd * wv;
;             if (F32OUT) *(f32x4*)(outf + (size_t)row * D_ + i * 256 + lane * 4) = y; else st_bf4(outb + (size_t)row * D_ + i * 256 + lane * 4, y); }
;     }
; }
.LBB0_2025:
	s_or_b64 exec, exec, s[6:7]
	s_waitcnt lgkmcnt(0)
	v_mov_b32_e32 v0, v192
	s_barrier
	s_mov_b32 s0, 0x8000
	v_mov_b32_e32 v0, v192
	s_nop 0
	v_ashrrev_i32_e32 v1, 6, v0
	v_add_u32_e32 v12, s92, v1
	v_cmp_gt_i32_e32 vcc, s0, v12
	s_and_saveexec_b64 s[8:9], vcc
	s_cbranch_execz .LBB0_2028
	v_mbcnt_hi_u32_b32 v1, -1, v193
	v_and_b32_e32 v2, 64, v1
	v_add_u32_e32 v2, 64, v2
	v_xor_b32_e32 v3, 32, v1
	v_cmp_lt_i32_e32 vcc, v3, v2
	s_mov_b64 s[0:1], 0x2000
	v_ashrrev_i32_e32 v13, 31, v12
	v_cndmask_b32_e32 v3, v1, v3, vcc
	v_lshlrev_b32_e32 v28, 2, v3
	v_xor_b32_e32 v3, 16, v1
	v_cmp_lt_i32_e32 vcc, v3, v2
	v_and_b32_e32 v4, 63, v0
	s_ashr_i32 s43, s42, 31
	v_cndmask_b32_e32 v3, v1, v3, vcc
	v_lshlrev_b32_e32 v29, 2, v3
	v_xor_b32_e32 v3, 8, v1
	v_cmp_lt_i32_e32 vcc, v3, v2
	s_lshl_b64 s[10:11], s[42:43], 13
	s_lshl_b64 s[12:13], s[42:43], 12
	v_cndmask_b32_e32 v3, v1, v3, vcc
	v_lshlrev_b32_e32 v30, 2, v3
	v_xor_b32_e32 v3, 4, v1
	v_cmp_lt_i32_e32 vcc, v3, v2
	s_mov_b64 s[14:15], 0
	v_mov_b32_e32 v34, 0x260
	v_cndmask_b32_e32 v3, v1, v3, vcc
	v_lshlrev_b32_e32 v31, 2, v3
	v_xor_b32_e32 v3, 2, v1
	v_cmp_lt_i32_e32 vcc, v3, v2
	s_nop 1
	v_cndmask_b32_e32 v3, v1, v3, vcc
	v_lshlrev_b32_e32 v32, 2, v3
	v_xor_b32_e32 v3, 1, v1
	v_cmp_lt_i32_e32 vcc, v3, v2
	s_nop 1
	v_cndmask_b32_e32 v1, v1, v3, vcc
	v_lshlrev_b32_e32 v33, 2, v1
	v_lshlrev_b32_e32 v1, 4, v0
	v_and_b32_e32 v2, 0x3f0, v1
	v_mov_b32_e32 v3, 0
	v_lshl_add_u64 v[2:3], s[40:41], 0, v[2:3]
	v_lshl_add_u64 v[14:15], v[2:3], 0, s[0:1]
	s_mov_b64 s[0:1], 0x3000
	v_lshl_add_u64 v[16:17], v[2:3], 0, s[0:1]
	s_mov_b64 s[0:1], 0x3400
	v_lshl_add_u64 v[18:19], v[2:3], 0, s[0:1]
	s_mov_b64 s[0:1], 0x3800
	v_lshl_add_u64 v[20:21], v[2:3], 0, s[0:1]
	s_mov_b64 s[0:1], 0x3c00
	v_lshl_add_u64 v[22:23], v[2:3], 0, s[0:1]
	v_lshlrev_b64 v[2:3], 13, v[12:13]
	v_lshl_or_b32 v2, v4, 4, v2
	v_lshl_add_u64 v[0:1], s[28:29], 0, v[2:3]
	s_mov_b64 s[0:1], 0x1000
	v_lshl_add_u64 v[24:25], v[0:1], 0, s[0:1]
	v_lshlrev_b64 v[0:1], 12, v[12:13]
	v_lshl_or_b32 v0, v4, 3, v0
	v_lshl_add_u64 v[0:1], s[30:31], 0, v[0:1]
	s_mov_b64 s[0:1], 0x15550800
	v_lshl_add_u64 v[26:27], v[0:1], 0, s[0:1]
	v_mov_b32_e32 v13, 0x358637bd
	s_mov_b32 s0, 0xf800000
	s_movk_i32 s1, 0x7fff
	global_load_dwordx4 v[100:103], v[14:15], off
	global_load_dwordx4 v[104:107], v[14:15], off offset:1024
	global_load_dwordx4 v[108:111], v[14:15], off offset:2048
	global_load_dwordx4 v[112:115], v[14:15], off offset:3072
	global_load_dwordx4 v[116:119], v[16:17], off
	global_load_dwordx4 v[120:123], v[18:19], off
	global_load_dwordx4 v[124:127], v[20:21], off
	global_load_dwordx4 v[128:131], v[22:23], off
	global_load_dwordx4 v[196:199], v[24:25], off offset:-4096
	global_load_dwordx4 v[200:203], v[24:25], off offset:-3072
	global_load_dwordx4 v[204:207], v[24:25], off offset:-2048
	global_load_dwordx4 v[208:211], v[24:25], off offset:-1024
	global_load_dwordx4 v[212:215], v[24:25], off
	global_load_dwordx4 v[216:219], v[24:25], off offset:1024
	global_load_dwordx4 v[220:223], v[24:25], off offset:2048
	global_load_dwordx4 v[224:227], v[24:25], off offset:3072
	v_add_u32_e32 v12, s42, v12
	v_lshl_add_u64 v[24:25], v[24:25], 0, s[10:11]
	s_waitcnt vmcnt(0)
.LBB0_2027:
	s_waitcnt vmcnt(8)
	v_mov_b32_e32 v36, v196
	v_mov_b32_e32 v37, v197
	v_mov_b32_e32 v38, v198
	v_mov_b32_e32 v39, v199
	v_mov_b32_e32 v40, v200
	v_mov_b32_e32 v41, v201
	v_mov_b32_e32 v42, v202
	v_mov_b32_e32 v43, v203
	v_mov_b32_e32 v44, v204
	v_mov_b32_e32 v45, v205
	v_mov_b32_e32 v46, v206
	v_mov_b32_e32 v47, v207
	v_mov_b32_e32 v48, v208
	v_mov_b32_e32 v49, v209
	v_mov_b32_e32 v50, v210
	v_mov_b32_e32 v51, v211
	v_mov_b32_e32 v52, v212
	v_mov_b32_e32 v53, v213
	v_mov_b32_e32 v54, v214
	v_mov_b32_e32 v55, v215
	v_mov_b32_e32 v8, v216
	v_mov_b32_e32 v9, v217
	v_mov_b32_e32 v10, v218
	v_mov_b32_e32 v11, v219
	v_mov_b32_e32 v4, v220
	v_mov_b32_e32 v5, v221
	v_mov_b32_e32 v6, v222
	v_mov_b32_e32 v7, v223
	v_mov_b32_e32 v0, v224
	v_mov_b32_e32 v1, v225
	v_mov_b32_e32 v2, v226
	v_mov_b32_e32 v3, v227
	v_cmp_lt_i32_e32 vcc, s1, v12
	s_or_b64 s[14:15], vcc, s[14:15]
	s_mov_b64 s[86:87], exec
	s_andn2_b64 exec, exec, s[14:15]
	global_load_dwordx4 v[196:199], v[24:25], off offset:-4096
	global_load_dwordx4 v[200:203], v[24:25], off offset:-3072
	global_load_dwordx4 v[204:207], v[24:25], off offset:-2048
	global_load_dwordx4 v[208:211], v[24:25], off offset:-1024
	global_load_dwordx4 v[212:215], v[24:25], off
	global_load_dwordx4 v[216:219], v[24:25], off offset:1024
	global_load_dwordx4 v[220:223], v[24:25], off offset:2048
	global_load_dwordx4 v[224:227], v[24:25], off offset:3072
	s_mov_b64 exec, s[86:87]
	v_add_u32_e32 v12, s42, v12
	v_lshl_add_u64 v[24:25], v[24:25], 0, s[10:11]
	v_mul_f32_e32 v35, v37, v37
	v_mul_f32_e32 v68, v41, v41
	v_mul_f32_e32 v69, v45, v45
	v_fmac_f32_e32 v35, v36, v36
	v_fmac_f32_e32 v68, v40, v40
	v_mul_f32_e32 v70, v49, v49
	v_fmac_f32_e32 v69, v44, v44
	v_fmac_f32_e32 v35, v38, v38
	v_fmac_f32_e32 v68, v42, v42
	v_mul_f32_e32 v71, v53, v53
	v_fmac_f32_e32 v70, v48, v48
	v_fmac_f32_e32 v69, v46, v46
	v_fmac_f32_e32 v35, v39, v39
	v_fmac_f32_e32 v68, v43, v43
	v_mul_f32_e32 v72, v9, v9
	v_mov_b32_e32 v62, v5
	v_mov_b32_e32 v63, v1
	v_fmac_f32_e32 v71, v52, v52
	v_fmac_f32_e32 v70, v50, v50
	v_fmac_f32_e32 v69, v47, v47
	v_add_f32_e32 v35, v35, v68
	v_mov_b32_e32 v60, v4
	v_mov_b32_e32 v61, v0
	v_fmac_f32_e32 v72, v8, v8
	v_pk_mul_f32 v[62:63], v[62:63], v[62:63]
	v_fmac_f32_e32 v71, v54, v54
	v_fmac_f32_e32 v70, v51, v51
	v_add_f32_e32 v35, v35, v69
	v_mov_b32_e32 v64, v6
	v_mov_b32_e32 v65, v2
	v_fmac_f32_e32 v72, v10, v10
	v_pk_fma_f32 v[60:61], v[60:61], v[60:61], v[62:63]
	v_fmac_f32_e32 v71, v55, v55
	v_add_f32_e32 v35, v35, v70
	v_mov_b32_e32 v66, v7
	v_mov_b32_e32 v67, v3
	v_fmac_f32_e32 v72, v11, v11
	v_pk_fma_f32 v[60:61], v[64:65], v[64:65], v[60:61]
	v_add_f32_e32 v35, v35, v71
	v_pk_fma_f32 v[60:61], v[66:67], v[66:67], v[60:61]
	v_add_f32_e32 v35, v35, v72
	v_add_f32_e32 v35, v35, v60
	v_add_f32_e32 v35, v35, v61
	ds_bpermute_b32 v60, v28, v35
	s_waitcnt lgkmcnt(0)
; __device__ __forceinline__ int opaque_tid() { int t = threadIdx.x; asm volatile("" : "+v"(t)); return t; }
; __device__ __forceinline__ void st_bf4(bf16_t* p, const f32x4 v) { u32x2 w; w.x = cvt_pk_bf16(v[0], v[1]); w.y = cvt_pk_bf16(v[2], v[3]); *(u32x2*)p = w; }
; __device__ __forceinline__ float wave_sum(float v) {
; #pragma unroll
;     for (int o = 32; o >= 1; o >>= 1) v += __shfl_xor(v, o);
;     return v;
; }
; template <bool F32OUT>
; __device__ __forceinline__ void rmsnorm_rows(const float* x, const float* w, bf16_t* outb, float* outf) {
;     const int tid_ = opaque_tid(); const int lane = tid_ & 63, gw = blockIdx.x * 8 + (tid_ >> 6), nw = gridDim.x * 8;
;     for (int row = gw; row < T_; row += nw) {
;         const float* xr = x + (size_t)row * D_; f32x4 v[8]; float ss = 0.f;
; #pragma unroll
;         for (int i = 0; i < 8; ++i) { v[i] = *(const f32x4*)(xr + i * 256 + lane * 4); ss += v[i][0] * v[i][0] + v[i][1] * v[i][1] + v[i][2] * v[i][2] + v[i][3] * v[i][3]; }
;         ss = wave_sum(ss);
;         const float rstd = 1.0f / sqrtf(ss * (1.0f / D_) + 1e-6f);
; #pragma unroll
;         for (int i = 0; i < 8; ++i) { const f32x4 wv = *(const f32x4*)(w + i * 256 + lane * 4); const f32x4 y = v[i] * rstd * wv;
;             if (F32OUT) *(f32x4*)(outf + (size_t)row * D_ + i * 256 + lane * 4) = y; else st_bf4(outb + (size_t)row * D_ + i * 256 + lane * 4, y); }
;     }
; }
	v_add_f32_e32 v35, v35, v60
	ds_bpermute_b32 v60, v29, v35
	s_waitcnt lgkmcnt(0)
	v_add_f32_e32 v35, v35, v60
	ds_bpermute_b32 v60, v30, v35
	s_waitcnt lgkmcnt(0)
	v_add_f32_e32 v35, v35, v60
	ds_bpermute_b32 v60, v31, v35
	s_waitcnt lgkmcnt(0)
	v_add_f32_e32 v35, v35, v60
	ds_bpermute_b32 v60, v32, v35
	s_waitcnt lgkmcnt(0)
	v_add_f32_e32 v35, v35, v60
	ds_bpermute_b32 v60, v33, v35
	s_waitcnt lgkmcnt(0)
	v_add_f32_e32 v35, v35, v60
	v_fmamk_f32 v35, v35, 0x3a000000, v13
	v_mul_f32_e32 v60, 0x4f800000, v35
	v_cmp_gt_f32_e32 vcc, s0, v35
	s_nop 1
	v_cndmask_b32_e32 v35, v35, v60, vcc
	v_sqrt_f32_e32 v60, v35
	s_nop 0
	v_add_u32_e32 v61, -1, v60
	v_add_u32_e32 v62, 1, v60
	v_fma_f32 v63, -v61, v60, v35
	v_fma_f32 v64, -v62, v60, v35
	v_cmp_ge_f32_e64 s[6:7], 0, v63
	s_nop 1
	v_cndmask_b32_e64 v60, v60, v61, s[6:7]
	v_cmp_lt_f32_e64 s[6:7], 0, v64
	s_nop 1
	v_cndmask_b32_e64 v60, v60, v62, s[6:7]
	v_mul_f32_e32 v61, 0x37800000, v60
	v_cndmask_b32_e32 v60, v60, v61, vcc
	v_cmp_class_f32_e32 vcc, v35, v34
	s_nop 1
	v_cndmask_b32_e32 v35, v60, v35, vcc
	v_div_scale_f32 v60, s[6:7], v35, v35, 1.0
	v_rcp_f32_e32 v62, v60
	v_div_scale_f32 v61, vcc, 1.0, v35, 1.0
	v_fma_f32 v63, -v60, v62, 1.0
	v_fmac_f32_e32 v62, v63, v62
	v_mul_f32_e32 v63, v61, v62
	v_fma_f32 v64, -v60, v63, v61
	v_fmac_f32_e32 v63, v64, v62
	v_fma_f32 v60, -v60, v63, v61
	v_div_fmas_f32 v60, v60, v62, v63
	v_div_fixup_f32 v60, v60, v35, 1.0
	v_pk_mul_f32 v[36:37], v[36:37], v[60:61] op_sel_hi:[1,0]
	v_pk_mul_f32 v[38:39], v[38:39], v[60:61] op_sel_hi:[1,0]
	v_pk_mul_f32 v[36:37], v[100:101], v[36:37]
	v_pk_mul_f32 v[38:39], v[102:103], v[38:39]
	v_cvt_pk_bf16_f32 v36, v36, v37
	s_nop 0
	v_cvt_pk_bf16_f32 v37, v38, v39
	global_store_dwordx2 v[26:27], v[36:37], off
	v_pk_mul_f32 v[40:41], v[40:41], v[60:61] op_sel_hi:[1,0]
	v_pk_mul_f32 v[42:43], v[42:43], v[60:61] op_sel_hi:[1,0]
	v_pk_mul_f32 v[40:41], v[104:105], v[40:41]
	v_pk_mul_f32 v[42:43], v[106:107], v[42:43]
	v_cvt_pk_bf16_f32 v40, v40, v41
	s_nop 0
	v_cvt_pk_bf16_f32 v41, v42, v43
	global_store_dwordx2 v[26:27], v[40:41], off offset:512
	v_pk_mul_f32 v[44:45], v[44:45], v[60:61] op_sel_hi:[1,0]
	v_pk_mul_f32 v[46:47], v[46:47], v[60:61] op_sel_hi:[1,0]
	v_pk_mul_f32 v[44:45], v[108:109], v[44:45]
	v_pk_mul_f32 v[46:47], v[110:111], v[46:47]
	v_cvt_pk_bf16_f32 v44, v44, v45
	s_nop 0
	v_cvt_pk_bf16_f32 v45, v46, v47
	global_store_dwordx2 v[26:27], v[44:45], off offset:1024
	v_pk_mul_f32 v[48:49], v[48:49], v[60:61] op_sel_hi:[1,0]
	v_pk_mul_f32 v[50:51], v[50:51], v[60:61] op_sel_hi:[1,0]
	v_pk_mul_f32 v[48:49], v[112:113], v[48:49]
	v_pk_mul_f32 v[50:51], v[114:115], v[50:51]
	v_cvt_pk_bf16_f32 v48, v48, v49
	s_nop 0
	v_cvt_pk_bf16_f32 v49, v50, v51
	global_store_dwordx2 v[26:27], v[48:49], off offset:1536
	v_pk_mul_f32 v[52:53], v[52:53], v[60:61] op_sel_hi:[1,0]
	v_pk_mul_f32 v[54:55], v[54:55], v[60:61] op_sel_hi:[1,0]
	v_pk_mul_f32 v[52:53], v[116:117], v[52:53]
	v_pk_mul_f32 v[54:55], v[118:119], v[54:55]
	v_cvt_pk_bf16_f32 v52, v52, v53
	s_nop 0
	v_cvt_pk_bf16_f32 v53, v54, v55
	global_store_dwordx2 v[26:27], v[52:53], off offset:2048
	v_pk_mul_f32 v[8:9], v[8:9], v[60:61] op_sel_hi:[1,0]
	v_pk_mul_f32 v[10:11], v[10:11], v[60:61] op_sel_hi:[1,0]
	v_pk_mul_f32 v[8:9], v[120:121], v[8:9]
	v_pk_mul_f32 v[10:11], v[122:123], v[10:11]
	v_cvt_pk_bf16_f32 v8, v8, v9
	s_nop 0
	v_cvt_pk_bf16_f32 v9, v10, v11
	global_store_dwordx2 v[26:27], v[8:9], off offset:2560
	v_pk_mul_f32 v[4:5], v[4:5], v[60:61] op_sel_hi:[1,0]
	v_pk_mul_f32 v[6:7], v[6:7], v[60:61] op_sel_hi:[1,0]
	v_pk_mul_f32 v[4:5], v[124:125], v[4:5]
	v_pk_mul_f32 v[6:7], v[126:127], v[6:7]
	v_cvt_pk_bf16_f32 v4, v4, v5
	s_nop 0
	v_cvt_pk_bf16_f32 v5, v6, v7
	global_store_dwordx2 v[26:27], v[4:5], off offset:3072
	v_pk_mul_f32 v[0:1], v[0:1], v[60:61] op_sel_hi:[1,0]
	v_pk_mul_f32 v[2:3], v[2:3], v[60:61] op_sel_hi:[1,0]
	v_pk_mul_f32 v[0:1], v[128:129], v[0:1]
	v_pk_mul_f32 v[2:3], v[130:131], v[2:3]
	v_cvt_pk_bf16_f32 v0, v0, v1
	s_nop 0
	v_cvt_pk_bf16_f32 v1, v2, v3
	global_store_dwordx2 v[26:27], v[0:1], off offset:3584
	v_lshl_add_u64 v[26:27], v[26:27], 0, s[12:13]
	s_andn2_b64 exec, exec, s[14:15]
	s_cbranch_execnz .LBB0_2027

; __device__ __forceinline__ int opaque_tid() { int t = threadIdx.x; asm volatile("" : "+v"(t)); return t; }
; __device__ __forceinline__ void st_bf4(bf16_t* p, const f32x4 v) { u32x2 w; w.x = cvt_pk_bf16(v[0], v[1]); w.y = cvt_pk_bf16(v[2], v[3]); *(u32x2*)p = w; }
; __device__ __forceinline__ float wave_sum(float v) {
; #pragma unroll
;     for (int o = 32; o >= 1; o >>= 1) v += __shfl_xor(v, o);
;     return v;
; }
; template <bool F32OUT>
; __device__ __forceinline__ void rmsnorm_rows(const float* x, const float* w, bf16_t* outb, float* outf) {
;     const int tid_ = opaque_tid(); const int lane = tid_ & 63, gw = blockIdx.x * 8 + (tid_ >> 6), nw = gridDim.x * 8;
;     for (int row = gw; row < T_; row += nw) {
;         const float* xr = x + (size_t)row * D_; f32x4 v[8]; float ss = 0.f;
; #pragma unroll
;         for (int i = 0; i < 8; ++i) { v[i] = *(const f32x4*)(xr + i * 256 + lane * 4); ss += v[i][0] * v[i][0] + v[i][1] * v[i][1] + v[i][2] * v[i][2] + v[i][3] * v[i][3]; }
;         ss = wave_sum(ss);
;         const float rstd = 1.0f / sqrtf(ss * (1.0f / D_) + 1e-6f);
; #pragma unroll
;         for (int i = 0; i < 8; ++i) { const f32x4 wv = *(const f32x4*)(w + i * 256 + lane * 4); const f32x4 y = v[i] * rstd * wv;
;             if (F32OUT) *(f32x4*)(outf + (size_t)row * D_ + i * 256 + lane * 4) = y; else st_bf4(outb + (size_t)row * D_ + i * 256 + lane * 4, y); }
;     }
; }
.LBB0_2224:
	s_or_b64 exec, exec, s[8:9]
	s_waitcnt lgkmcnt(0)
	v_mov_b32_e32 v0, v192
	s_barrier
	s_mov_b32 s0, 0x8000
	v_mov_b32_e32 v0, v192
	s_nop 0
	v_ashrrev_i32_e32 v1, 6, v0
	v_add_u32_e32 v12, s92, v1
	v_cmp_gt_i32_e32 vcc, s0, v12
	s_and_saveexec_b64 s[10:11], vcc
	s_cbranch_execz .LBB0_2227
	v_mbcnt_hi_u32_b32 v1, -1, v193
	v_and_b32_e32 v2, 64, v1
	v_add_u32_e32 v2, 64, v2
	v_xor_b32_e32 v3, 32, v1
	v_cmp_lt_i32_e32 vcc, v3, v2
	s_mov_b64 s[0:1], 0x4000
	v_ashrrev_i32_e32 v13, 31, v12
	v_cndmask_b32_e32 v3, v1, v3, vcc
	v_lshlrev_b32_e32 v28, 2, v3
	v_xor_b32_e32 v3, 16, v1
	v_cmp_lt_i32_e32 vcc, v3, v2
	v_and_b32_e32 v4, 63, v0
	s_ashr_i32 s43, s42, 31
	v_cndmask_b32_e32 v3, v1, v3, vcc
	v_lshlrev_b32_e32 v29, 2, v3
	v_xor_b32_e32 v3, 8, v1
	v_cmp_lt_i32_e32 vcc, v3, v2
	s_lshl_b64 s[12:13], s[42:43], 13
	s_lshl_b64 s[14:15], s[42:43], 12
	v_cndmask_b32_e32 v3, v1, v3, vcc
	v_lshlrev_b32_e32 v30, 2, v3
	v_xor_b32_e32 v3, 4, v1
	v_cmp_lt_i32_e32 vcc, v3, v2
	s_mov_b64 s[16:17], 0
	v_mov_b32_e32 v34, 0x260
	v_cndmask_b32_e32 v3, v1, v3, vcc
	v_lshlrev_b32_e32 v31, 2, v3
	v_xor_b32_e32 v3, 2, v1
	v_cmp_lt_i32_e32 vcc, v3, v2
	s_nop 1
	v_cndmask_b32_e32 v3, v1, v3, vcc
	v_lshlrev_b32_e32 v32, 2, v3
	v_xor_b32_e32 v3, 1, v1
	v_cmp_lt_i32_e32 vcc, v3, v2
	s_nop 1
	v_cndmask_b32_e32 v1, v1, v3, vcc
	v_lshlrev_b32_e32 v33, 2, v1
	v_lshlrev_b32_e32 v1, 4, v0
	v_and_b32_e32 v2, 0x3f0, v1
	v_mov_b32_e32 v3, 0
	v_lshl_add_u64 v[2:3], s[40:41], 0, v[2:3]
	v_lshl_add_u64 v[14:15], v[2:3], 0, s[0:1]
	s_mov_b64 s[0:1], 0x5000
	v_lshl_add_u64 v[16:17], v[2:3], 0, s[0:1]
	s_mov_b64 s[0:1], 0x5400
	v_lshl_add_u64 v[18:19], v[2:3], 0, s[0:1]
	s_mov_b64 s[0:1], 0x5800
	v_lshl_add_u64 v[20:21], v[2:3], 0, s[0:1]
	s_mov_b64 s[0:1], 0x5c00
	v_lshl_add_u64 v[22:23], v[2:3], 0, s[0:1]
	v_lshlrev_b64 v[2:3], 13, v[12:13]
	v_lshl_or_b32 v2, v4, 4, v2
	v_lshl_add_u64 v[0:1], s[28:29], 0, v[2:3]
	s_mov_b64 s[0:1], 0x1000
	v_lshl_add_u64 v[24:25], v[0:1], 0, s[0:1]
	v_lshlrev_b64 v[0:1], 12, v[12:13]
	v_lshl_or_b32 v0, v4, 3, v0
	v_lshl_add_u64 v[0:1], s[30:31], 0, v[0:1]
	s_mov_b64 s[0:1], 0x15550800
	v_lshl_add_u64 v[26:27], v[0:1], 0, s[0:1]
	v_mov_b32_e32 v13, 0x358637bd
	s_mov_b32 s0, 0xf800000
	s_movk_i32 s1, 0x7fff
	global_load_dwordx4 v[100:103], v[14:15], off
	global_load_dwordx4 v[104:107], v[14:15], off offset:1024
	global_load_dwordx4 v[108:111], v[14:15], off offset:2048
	global_load_dwordx4 v[112:115], v[14:15], off offset:3072
	global_load_dwordx4 v[116:119], v[16:17], off
	global_load_dwordx4 v[120:123], v[18:19], off
	global_load_dwordx4 v[124:127], v[20:21], off
	global_load_dwordx4 v[128:131], v[22:23], off
	global_load_dwordx4 v[196:199], v[24:25], off offset:-4096
	global_load_dwordx4 v[200:203], v[24:25], off offset:-3072
	global_load_dwordx4 v[204:207], v[24:25], off offset:-2048
	global_load_dwordx4 v[208:211], v[24:25], off offset:-1024
	global_load_dwordx4 v[212:215], v[24:25], off
	global_load_dwordx4 v[216:219], v[24:25], off offset:1024
	global_load_dwordx4 v[220:223], v[24:25], off offset:2048
	global_load_dwordx4 v[224:227], v[24:25], off offset:3072
	v_add_u32_e32 v12, s42, v12
	v_lshl_add_u64 v[24:25], v[24:25], 0, s[12:13]
	s_waitcnt vmcnt(0)
.LBB0_2226:
	s_waitcnt vmcnt(8)
	v_mov_b32_e32 v36, v196
	v_mov_b32_e32 v37, v197
	v_mov_b32_e32 v38, v198
	v_mov_b32_e32 v39, v199
	v_mov_b32_e32 v40, v200
	v_mov_b32_e32 v41, v201
	v_mov_b32_e32 v42, v202
	v_mov_b32_e32 v43, v203
	v_mov_b32_e32 v44, v204
	v_mov_b32_e32 v45, v205
	v_mov_b32_e32 v46, v206
	v_mov_b32_e32 v47, v207
	v_mov_b32_e32 v48, v208
	v_mov_b32_e32 v49, v209
	v_mov_b32_e32 v50, v210
	v_mov_b32_e32 v51, v211
	v_mov_b32_e32 v52, v212
	v_mov_b32_e32 v53, v213
	v_mov_b32_e32 v54, v214
	v_mov_b32_e32 v55, v215
	v_mov_b32_e32 v8, v216
	v_mov_b32_e32 v9, v217
	v_mov_b32_e32 v10, v218
	v_mov_b32_e32 v11, v219
	v_mov_b32_e32 v4, v220
	v_mov_b32_e32 v5, v221
	v_mov_b32_e32 v6, v222
	v_mov_b32_e32 v7, v223
	v_mov_b32_e32 v0, v224
	v_mov_b32_e32 v1, v225
	v_mov_b32_e32 v2, v226
	v_mov_b32_e32 v3, v227
	v_cmp_lt_i32_e32 vcc, s1, v12
	s_or_b64 s[16:17], vcc, s[16:17]
	s_mov_b64 s[86:87], exec
	s_andn2_b64 exec, exec, s[16:17]
	global_load_dwordx4 v[196:199], v[24:25], off offset:-4096
	global_load_dwordx4 v[200:203], v[24:25], off offset:-3072
	global_load_dwordx4 v[204:207], v[24:25], off offset:-2048
	global_load_dwordx4 v[208:211], v[24:25], off offset:-1024
	global_load_dwordx4 v[212:215], v[24:25], off
	global_load_dwordx4 v[216:219], v[24:25], off offset:1024
	global_load_dwordx4 v[220:223], v[24:25], off offset:2048
	global_load_dwordx4 v[224:227], v[24:25], off offset:3072
	s_mov_b64 exec, s[86:87]
	v_add_u32_e32 v12, s42, v12
	v_lshl_add_u64 v[24:25], v[24:25], 0, s[12:13]
	v_mul_f32_e32 v35, v37, v37
	v_mul_f32_e32 v68, v41, v41
	v_mul_f32_e32 v69, v45, v45
	v_fmac_f32_e32 v35, v36, v36
	v_fmac_f32_e32 v68, v40, v40
	v_mul_f32_e32 v70, v49, v49
	v_fmac_f32_e32 v69, v44, v44
	v_fmac_f32_e32 v35, v38, v38
	v_fmac_f32_e32 v68, v42, v42
	v_mul_f32_e32 v71, v53, v53
	v_fmac_f32_e32 v70, v48, v48
	v_fmac_f32_e32 v69, v46, v46
	v_fmac_f32_e32 v35, v39, v39
	v_fmac_f32_e32 v68, v43, v43
	v_mul_f32_e32 v72, v9, v9
	v_mov_b32_e32 v62, v5
	v_mov_b32_e32 v63, v1
	v_fmac_f32_e32 v71, v52, v52
	v_fmac_f32_e32 v70, v50, v50
	v_fmac_f32_e32 v69, v47, v47
	v_add_f32_e32 v35, v35, v68
	v_mov_b32_e32 v60, v4
	v_mov_b32_e32 v61, v0
	v_fmac_f32_e32 v72, v8, v8
	v_pk_mul_f32 v[62:63], v[62:63], v[62:63]
	v_fmac_f32_e32 v71, v54, v54
	v_fmac_f32_e32 v70, v51, v51
	v_add_f32_e32 v35, v35, v69
	v_mov_b32_e32 v64, v6
	v_mov_b32_e32 v65, v2
	v_fmac_f32_e32 v72, v10, v10
	v_pk_fma_f32 v[60:61], v[60:61], v[60:61], v[62:63]
	v_fmac_f32_e32 v71, v55, v55
	v_add_f32_e32 v35, v35, v70
	v_mov_b32_e32 v66, v7
	v_mov_b32_e32 v67, v3
	v_fmac_f32_e32 v72, v11, v11
	v_pk_fma_f32 v[60:61], v[64:65], v[64:65], v[60:61]
	v_add_f32_e32 v35, v35, v71
	v_pk_fma_f32 v[60:61], v[66:67], v[66:67], v[60:61]
	v_add_f32_e32 v35, v35, v72
	v_add_f32_e32 v35, v35, v60
	v_add_f32_e32 v35, v35, v61
	ds_bpermute_b32 v60, v28, v35
	s_waitcnt lgkmcnt(0)
; __device__ __forceinline__ int opaque_tid() { int t = threadIdx.x; asm volatile("" : "+v"(t)); return t; }
; __device__ __forceinline__ void st_bf4(bf16_t* p, const f32x4 v) { u32x2 w; w.x = cvt_pk_bf16(v[0], v[1]); w.y = cvt_pk_bf16(v[2], v[3]); *(u32x2*)p = w; }
; __device__ __forceinline__ float wave_sum(float v) {
; #pragma unroll
;     for (int o = 32; o >= 1; o >>= 1) v += __shfl_xor(v, o);
;     return v;
; }
; template <bool F32OUT>
; __device__ __forceinline__ void rmsnorm_rows(const float* x, const float* w, bf16_t* outb, float* outf) {
;     const int tid_ = opaque_tid(); const int lane = tid_ & 63, gw = blockIdx.x * 8 + (tid_ >> 6), nw = gridDim.x * 8;
;     for (int row = gw; row < T_; row += nw) {
;         const float* xr = x + (size_t)row * D_; f32x4 v[8]; float ss = 0.f;
; #pragma unroll
;         for (int i = 0; i < 8; ++i) { v[i] = *(const f32x4*)(xr + i * 256 + lane * 4); ss += v[i][0] * v[i][0] + v[i][1] * v[i][1] + v[i][2] * v[i][2] + v[i][3] * v[i][3]; }
;         ss = wave_sum(ss);
;         const float rstd = 1.0f / sqrtf(ss * (1.0f / D_) + 1e-6f);
; #pragma unroll
;         for (int i = 0; i < 8; ++i) { const f32x4 wv = *(const f32x4*)(w + i * 256 + lane * 4); const f32x4 y = v[i] * rstd * wv;
;             if (F32OUT) *(f32x4*)(outf + (size_t)row * D_ + i * 256 + lane * 4) = y; else st_bf4(outb + (size_t)row * D_ + i * 256 + lane * 4, y); }
;     }
; }
	v_add_f32_e32 v35, v35, v60
	ds_bpermute_b32 v60, v29, v35
	s_waitcnt lgkmcnt(0)
	v_add_f32_e32 v35, v35, v60
	ds_bpermute_b32 v60, v30, v35
	s_waitcnt lgkmcnt(0)
	v_add_f32_e32 v35, v35, v60
	ds_bpermute_b32 v60, v31, v35
	s_waitcnt lgkmcnt(0)
	v_add_f32_e32 v35, v35, v60
	ds_bpermute_b32 v60, v32, v35
	s_waitcnt lgkmcnt(0)
	v_add_f32_e32 v35, v35, v60
	ds_bpermute_b32 v60, v33, v35
	s_waitcnt lgkmcnt(0)
	v_add_f32_e32 v35, v35, v60
	v_fmamk_f32 v35, v35, 0x3a000000, v13
	v_mul_f32_e32 v60, 0x4f800000, v35
	v_cmp_gt_f32_e32 vcc, s0, v35
	s_nop 1
	v_cndmask_b32_e32 v35, v35, v60, vcc
	v_sqrt_f32_e32 v60, v35
	s_nop 0
	v_add_u32_e32 v61, -1, v60
	v_add_u32_e32 v62, 1, v60
	v_fma_f32 v63, -v61, v60, v35
	v_fma_f32 v64, -v62, v60, v35
	v_cmp_ge_f32_e64 s[8:9], 0, v63
	s_nop 1
	v_cndmask_b32_e64 v60, v60, v61, s[8:9]
	v_cmp_lt_f32_e64 s[8:9], 0, v64
	s_nop 1
	v_cndmask_b32_e64 v60, v60, v62, s[8:9]
	v_mul_f32_e32 v61, 0x37800000, v60
	v_cndmask_b32_e32 v60, v60, v61, vcc
	v_cmp_class_f32_e32 vcc, v35, v34
	s_nop 1
	v_cndmask_b32_e32 v35, v60, v35, vcc
	v_div_scale_f32 v60, s[8:9], v35, v35, 1.0
	v_rcp_f32_e32 v62, v60
	v_div_scale_f32 v61, vcc, 1.0, v35, 1.0
	v_fma_f32 v63, -v60, v62, 1.0
	v_fmac_f32_e32 v62, v63, v62
	v_mul_f32_e32 v63, v61, v62
	v_fma_f32 v64, -v60, v63, v61
	v_fmac_f32_e32 v63, v64, v62
	v_fma_f32 v60, -v60, v63, v61
	v_div_fmas_f32 v60, v60, v62, v63
	v_div_fixup_f32 v60, v60, v35, 1.0
	v_pk_mul_f32 v[36:37], v[36:37], v[60:61] op_sel_hi:[1,0]
	v_pk_mul_f32 v[38:39], v[38:39], v[60:61] op_sel_hi:[1,0]
	v_pk_mul_f32 v[36:37], v[100:101], v[36:37]
	v_pk_mul_f32 v[38:39], v[102:103], v[38:39]
	v_cvt_pk_bf16_f32 v36, v36, v37
	s_nop 0
	v_cvt_pk_bf16_f32 v37, v38, v39
	global_store_dwordx2 v[26:27], v[36:37], off
	v_pk_mul_f32 v[40:41], v[40:41], v[60:61] op_sel_hi:[1,0]
	v_pk_mul_f32 v[42:43], v[42:43], v[60:61] op_sel_hi:[1,0]
	v_pk_mul_f32 v[40:41], v[104:105], v[40:41]
	v_pk_mul_f32 v[42:43], v[106:107], v[42:43]
	v_cvt_pk_bf16_f32 v40, v40, v41
	s_nop 0
	v_cvt_pk_bf16_f32 v41, v42, v43
	global_store_dwordx2 v[26:27], v[40:41], off offset:512
	v_pk_mul_f32 v[44:45], v[44:45], v[60:61] op_sel_hi:[1,0]
	v_pk_mul_f32 v[46:47], v[46:47], v[60:61] op_sel_hi:[1,0]
	v_pk_mul_f32 v[44:45], v[108:109], v[44:45]
	v_pk_mul_f32 v[46:47], v[110:111], v[46:47]
	v_cvt_pk_bf16_f32 v44, v44, v45
	s_nop 0
	v_cvt_pk_bf16_f32 v45, v46, v47
	global_store_dwordx2 v[26:27], v[44:45], off offset:1024
	v_pk_mul_f32 v[48:49], v[48:49], v[60:61] op_sel_hi:[1,0]
	v_pk_mul_f32 v[50:51], v[50:51], v[60:61] op_sel_hi:[1,0]
	v_pk_mul_f32 v[48:49], v[112:113], v[48:49]
	v_pk_mul_f32 v[50:51], v[114:115], v[50:51]
	v_cvt_pk_bf16_f32 v48, v48, v49
	s_nop 0
	v_cvt_pk_bf16_f32 v49, v50, v51
	global_store_dwordx2 v[26:27], v[48:49], off offset:1536
	v_pk_mul_f32 v[52:53], v[52:53], v[60:61] op_sel_hi:[1,0]
	v_pk_mul_f32 v[54:55], v[54:55], v[60:61] op_sel_hi:[1,0]
	v_pk_mul_f32 v[52:53], v[116:117], v[52:53]
	v_pk_mul_f32 v[54:55], v[118:119], v[54:55]
	v_cvt_pk_bf16_f32 v52, v52, v53
	s_nop 0
	v_cvt_pk_bf16_f32 v53, v54, v55
	global_store_dwordx2 v[26:27], v[52:53], off offset:2048
	v_pk_mul_f32 v[8:9], v[8:9], v[60:61] op_sel_hi:[1,0]
	v_pk_mul_f32 v[10:11], v[10:11], v[60:61] op_sel_hi:[1,0]
	v_pk_mul_f32 v[8:9], v[120:121], v[8:9]
	v_pk_mul_f32 v[10:11], v[122:123], v[10:11]
	v_cvt_pk_bf16_f32 v8, v8, v9
	s_nop 0
	v_cvt_pk_bf16_f32 v9, v10, v11
	global_store_dwordx2 v[26:27], v[8:9], off offset:2560
	v_pk_mul_f32 v[4:5], v[4:5], v[60:61] op_sel_hi:[1,0]
	v_pk_mul_f32 v[6:7], v[6:7], v[60:61] op_sel_hi:[1,0]
	v_pk_mul_f32 v[4:5], v[124:125], v[4:5]
	v_pk_mul_f32 v[6:7], v[126:127], v[6:7]
	v_cvt_pk_bf16_f32 v4, v4, v5
	s_nop 0
	v_cvt_pk_bf16_f32 v5, v6, v7
	global_store_dwordx2 v[26:27], v[4:5], off offset:3072
	v_pk_mul_f32 v[0:1], v[0:1], v[60:61] op_sel_hi:[1,0]
	v_pk_mul_f32 v[2:3], v[2:3], v[60:61] op_sel_hi:[1,0]
	v_pk_mul_f32 v[0:1], v[128:129], v[0:1]
	v_pk_mul_f32 v[2:3], v[130:131], v[2:3]
	v_cvt_pk_bf16_f32 v0, v0, v1
	s_nop 0
	v_cvt_pk_bf16_f32 v1, v2, v3
	global_store_dwordx2 v[26:27], v[0:1], off offset:3584
	v_lshl_add_u64 v[26:27], v[26:27], 0, s[14:15]
	s_andn2_b64 exec, exec, s[16:17]
	s_cbranch_execnz .LBB0_2226

; __device__ __forceinline__ int opaque_tid() { int t = threadIdx.x; asm volatile("" : "+v"(t)); return t; }
; __device__ __forceinline__ void st_bf4(bf16_t* p, const f32x4 v) { u32x2 w; w.x = cvt_pk_bf16(v[0], v[1]); w.y = cvt_pk_bf16(v[2], v[3]); *(u32x2*)p = w; }
; __device__ __forceinline__ float wave_sum(float v) {
; #pragma unroll
;     for (int o = 32; o >= 1; o >>= 1) v += __shfl_xor(v, o);
;     return v;
; }
; template <bool F32OUT>
; __device__ __forceinline__ void rmsnorm_rows(const float* x, const float* w, bf16_t* outb, float* outf) {
;     const int tid_ = opaque_tid(); const int lane = tid_ & 63, gw = blockIdx.x * 8 + (tid_ >> 6), nw = gridDim.x * 8;
;     for (int row = gw; row < T_; row += nw) {
;         const float* xr = x + (size_t)row * D_; f32x4 v[8]; float ss = 0.f;
; #pragma unroll
;         for (int i = 0; i < 8; ++i) { v[i] = *(const f32x4*)(xr + i * 256 + lane * 4); ss += v[i][0] * v[i][0] + v[i][1] * v[i][1] + v[i][2] * v[i][2] + v[i][3] * v[i][3]; }
;         ss = wave_sum(ss);
;         const float rstd = 1.0f / sqrtf(ss * (1.0f / D_) + 1e-6f);
; #pragma unroll
;         for (int i = 0; i < 8; ++i) { const f32x4 wv = *(const f32x4*)(w + i * 256 + lane * 4); const f32x4 y = v[i] * rstd * wv;
;             if (F32OUT) *(f32x4*)(outf + (size_t)row * D_ + i * 256 + lane * 4) = y; else st_bf4(outb + (size_t)row * D_ + i * 256 + lane * 4, y); }
;     }
; }
.LBB0_2423:
	s_or_b64 exec, exec, s[8:9]
	s_waitcnt lgkmcnt(0)
	v_mov_b32_e32 v0, v192
	s_barrier
	s_mov_b32 s0, 0x8000
	v_ashrrev_i32_e32 v1, 6, v0
	v_add_u32_e32 v12, s92, v1
	v_cmp_gt_i32_e32 vcc, s0, v12
	s_and_saveexec_b64 s[10:11], vcc
	s_cbranch_execz .LBB0_2426
	v_mbcnt_hi_u32_b32 v1, -1, v193
	v_and_b32_e32 v2, 64, v1
	v_add_u32_e32 v2, 64, v2
	v_xor_b32_e32 v3, 32, v1
	v_cmp_lt_i32_e32 vcc, v3, v2
	s_mov_b64 s[0:1], 0x2000
	v_ashrrev_i32_e32 v13, 31, v12
	v_cndmask_b32_e32 v3, v1, v3, vcc
	v_lshlrev_b32_e32 v28, 2, v3
	v_xor_b32_e32 v3, 16, v1
	v_cmp_lt_i32_e32 vcc, v3, v2
	v_and_b32_e32 v4, 63, v0
	s_ashr_i32 s43, s42, 31
	v_cndmask_b32_e32 v3, v1, v3, vcc
	v_lshlrev_b32_e32 v29, 2, v3
	v_xor_b32_e32 v3, 8, v1
	v_cmp_lt_i32_e32 vcc, v3, v2
	s_lshl_b64 s[12:13], s[42:43], 13
	s_lshl_b64 s[14:15], s[42:43], 12
	v_cndmask_b32_e32 v3, v1, v3, vcc
	v_lshlrev_b32_e32 v30, 2, v3
	v_xor_b32_e32 v3, 4, v1
	v_cmp_lt_i32_e32 vcc, v3, v2
	s_mov_b64 s[16:17], 0
	v_mov_b32_e32 v34, 0x260
	v_cndmask_b32_e32 v3, v1, v3, vcc
	v_lshlrev_b32_e32 v31, 2, v3
	v_xor_b32_e32 v3, 2, v1
	v_cmp_lt_i32_e32 vcc, v3, v2
	s_nop 1
	v_cndmask_b32_e32 v3, v1, v3, vcc
	v_lshlrev_b32_e32 v32, 2, v3
	v_xor_b32_e32 v3, 1, v1
	v_cmp_lt_i32_e32 vcc, v3, v2
	s_nop 1
	v_cndmask_b32_e32 v1, v1, v3, vcc
	v_lshlrev_b32_e32 v33, 2, v1
	v_lshlrev_b32_e32 v1, 4, v0
	v_and_b32_e32 v2, 0x3f0, v1
	v_mov_b32_e32 v3, 0
	v_lshl_add_u64 v[2:3], s[46:47], 0, v[2:3]
	v_lshl_add_u64 v[14:15], v[2:3], 0, s[0:1]
	s_mov_b64 s[0:1], 0x3000
	v_lshl_add_u64 v[16:17], v[2:3], 0, s[0:1]
	s_mov_b64 s[0:1], 0x3400
	v_lshl_add_u64 v[18:19], v[2:3], 0, s[0:1]
	s_mov_b64 s[0:1], 0x3800
	v_lshl_add_u64 v[20:21], v[2:3], 0, s[0:1]
	s_mov_b64 s[0:1], 0x3c00
	v_lshl_add_u64 v[22:23], v[2:3], 0, s[0:1]
	v_lshlrev_b64 v[2:3], 13, v[12:13]
	v_lshl_or_b32 v2, v4, 4, v2
	v_lshl_add_u64 v[0:1], s[28:29], 0, v[2:3]
	s_mov_b64 s[0:1], 0x1000
	v_lshl_add_u64 v[24:25], v[0:1], 0, s[0:1]
	v_lshlrev_b64 v[0:1], 12, v[12:13]
	v_lshl_or_b32 v0, v4, 3, v0
	v_lshl_add_u64 v[0:1], s[30:31], 0, v[0:1]
	s_mov_b64 s[0:1], 0x15550800
	v_lshl_add_u64 v[26:27], v[0:1], 0, s[0:1]
	v_mov_b32_e32 v13, 0x358637bd
	s_mov_b32 s0, 0xf800000
	s_movk_i32 s1, 0x7fff
	global_load_dwordx4 v[100:103], v[14:15], off
	global_load_dwordx4 v[104:107], v[14:15], off offset:1024
	global_load_dwordx4 v[108:111], v[14:15], off offset:2048
	global_load_dwordx4 v[112:115], v[14:15], off offset:3072
	global_load_dwordx4 v[116:119], v[16:17], off
	global_load_dwordx4 v[120:123], v[18:19], off
	global_load_dwordx4 v[124:127], v[20:21], off
	global_load_dwordx4 v[128:131], v[22:23], off
	global_load_dwordx4 v[196:199], v[24:25], off offset:-4096
	global_load_dwordx4 v[200:203], v[24:25], off offset:-3072
	global_load_dwordx4 v[204:207], v[24:25], off offset:-2048
	global_load_dwordx4 v[208:211], v[24:25], off offset:-1024
	global_load_dwordx4 v[212:215], v[24:25], off
	global_load_dwordx4 v[216:219], v[24:25], off offset:1024
	global_load_dwordx4 v[220:223], v[24:25], off offset:2048
	global_load_dwordx4 v[224:227], v[24:25], off offset:3072
	v_add_u32_e32 v12, s42, v12
	v_lshl_add_u64 v[24:25], v[24:25], 0, s[12:13]
	s_waitcnt vmcnt(0)

; __device__ __forceinline__ int opaque_tid() { int t = threadIdx.x; asm volatile("" : "+v"(t)); return t; }
; __device__ __forceinline__ void st_bf4(bf16_t* p, const f32x4 v) { u32x2 w; w.x = cvt_pk_bf16(v[0], v[1]); w.y = cvt_pk_bf16(v[2], v[3]); *(u32x2*)p = w; }
; __device__ __forceinline__ float wave_sum(float v) {
; #pragma unroll
;     for (int o = 32; o >= 1; o >>= 1) v += __shfl_xor(v, o);
;     return v;
; }
; template <bool F32OUT>
; __device__ __forceinline__ void rmsnorm_rows(const float* x, const float* w, bf16_t* outb, float* outf) {
;     const int tid_ = opaque_tid(); const int lane = tid_ & 63, gw = blockIdx.x * 8 + (tid_ >> 6), nw = gridDim.x * 8;
;     for (int row = gw; row < T_; row += nw) {
;         const float* xr = x + (size_t)row * D_; f32x4 v[8]; float ss = 0.f;
; #pragma unroll
;         for (int i = 0; i < 8; ++i) { v[i] = *(const f32x4*)(xr + i * 256 + lane * 4); ss += v[i][0] * v[i][0] + v[i][1] * v[i][1] + v[i][2] * v[i][2] + v[i][3] * v[i][3]; }
;         ss = wave_sum(ss);
;         const float rstd = 1.0f / sqrtf(ss * (1.0f / D_) + 1e-6f);
; #pragma unroll
;         for (int i = 0; i < 8; ++i) { const f32x4 wv = *(const f32x4*)(w + i * 256 + lane * 4); const f32x4 y = v[i] * rstd * wv;
;             if (F32OUT) *(f32x4*)(outf + (size_t)row * D_ + i * 256 + lane * 4) = y; else st_bf4(outb + (size_t)row * D_ + i * 256 + lane * 4, y); }
;     }
; }
.LBB0_3022:
	s_or_b64 exec, exec, s[8:9]
	s_waitcnt lgkmcnt(0)
	v_mov_b32_e32 v0, v192
	s_barrier
	s_mov_b32 s0, 0x8000
	v_mov_b32_e32 v0, v192
	s_nop 0
	v_ashrrev_i32_e32 v1, 6, v0
	v_add_u32_e32 v12, s92, v1
	v_cmp_gt_i32_e32 vcc, s0, v12
	s_and_saveexec_b64 s[10:11], vcc
	s_cbranch_execz .LBB0_3025
	v_mbcnt_hi_u32_b32 v1, -1, v193
	v_and_b32_e32 v2, 64, v1
	v_add_u32_e32 v2, 64, v2
	v_xor_b32_e32 v3, 32, v1
	v_cmp_lt_i32_e32 vcc, v3, v2
	s_mov_b64 s[0:1], 0x6000
	v_ashrrev_i32_e32 v13, 31, v12
	v_cndmask_b32_e32 v3, v1, v3, vcc
	v_lshlrev_b32_e32 v28, 2, v3
	v_xor_b32_e32 v3, 16, v1
	v_cmp_lt_i32_e32 vcc, v3, v2
	v_and_b32_e32 v4, 63, v0
	s_ashr_i32 s43, s42, 31
	v_cndmask_b32_e32 v3, v1, v3, vcc
	v_lshlrev_b32_e32 v29, 2, v3
	v_xor_b32_e32 v3, 8, v1
	v_cmp_lt_i32_e32 vcc, v3, v2
	s_lshl_b64 s[12:13], s[42:43], 13
	s_lshl_b64 s[14:15], s[42:43], 12
	v_cndmask_b32_e32 v3, v1, v3, vcc
	v_lshlrev_b32_e32 v30, 2, v3
	v_xor_b32_e32 v3, 4, v1
	v_cmp_lt_i32_e32 vcc, v3, v2
	s_mov_b64 s[16:17], 0
	v_mov_b32_e32 v34, 0x260
	v_cndmask_b32_e32 v3, v1, v3, vcc
	v_lshlrev_b32_e32 v31, 2, v3
	v_xor_b32_e32 v3, 2, v1
	v_cmp_lt_i32_e32 vcc, v3, v2
	s_nop 1
	v_cndmask_b32_e32 v3, v1, v3, vcc
	v_lshlrev_b32_e32 v32, 2, v3
	v_xor_b32_e32 v3, 1, v1
	v_cmp_lt_i32_e32 vcc, v3, v2
	s_nop 1
	v_cndmask_b32_e32 v1, v1, v3, vcc
	v_lshlrev_b32_e32 v33, 2, v1
	v_lshlrev_b32_e32 v1, 4, v0
	v_and_b32_e32 v2, 0x3f0, v1
	v_mov_b32_e32 v3, 0
	v_lshl_add_u64 v[2:3], s[40:41], 0, v[2:3]
	v_lshl_add_u64 v[14:15], v[2:3], 0, s[0:1]
	s_mov_b64 s[0:1], 0x7000
	v_lshl_add_u64 v[16:17], v[2:3], 0, s[0:1]
	s_mov_b64 s[0:1], 0x7400
	v_lshl_add_u64 v[18:19], v[2:3], 0, s[0:1]
	s_mov_b64 s[0:1], 0x7800
	v_lshl_add_u64 v[20:21], v[2:3], 0, s[0:1]
	s_mov_b64 s[0:1], 0x7c00
	v_lshl_add_u64 v[22:23], v[2:3], 0, s[0:1]
	v_lshlrev_b64 v[2:3], 13, v[12:13]
	v_lshl_or_b32 v2, v4, 4, v2
	v_lshl_add_u64 v[0:1], s[28:29], 0, v[2:3]
	s_mov_b64 s[0:1], 0x1000
	v_lshl_add_u64 v[24:25], v[0:1], 0, s[0:1]
	v_lshlrev_b64 v[0:1], 12, v[12:13]
	v_lshl_or_b32 v0, v4, 3, v0
	v_lshl_add_u64 v[0:1], s[30:31], 0, v[0:1]
	s_mov_b64 s[0:1], 0x15550800
	v_lshl_add_u64 v[26:27], v[0:1], 0, s[0:1]
	v_mov_b32_e32 v13, 0x358637bd
	s_mov_b32 s0, 0xf800000
	s_movk_i32 s1, 0x7fff
	global_load_dwordx4 v[100:103], v[14:15], off
	global_load_dwordx4 v[104:107], v[14:15], off offset:1024
	global_load_dwordx4 v[108:111], v[14:15], off offset:2048
	global_load_dwordx4 v[112:115], v[14:15], off offset:3072
	global_load_dwordx4 v[116:119], v[16:17], off
	global_load_dwordx4 v[120:123], v[18:19], off
	global_load_dwordx4 v[124:127], v[20:21], off
	global_load_dwordx4 v[128:131], v[22:23], off
	global_load_dwordx4 v[196:199], v[24:25], off offset:-4096
	global_load_dwordx4 v[200:203], v[24:25], off offset:-3072
	global_load_dwordx4 v[204:207], v[24:25], off offset:-2048
	global_load_dwordx4 v[208:211], v[24:25], off offset:-1024
	global_load_dwordx4 v[212:215], v[24:25], off
	global_load_dwordx4 v[216:219], v[24:25], off offset:1024
	global_load_dwordx4 v[220:223], v[24:25], off offset:2048
	global_load_dwordx4 v[224:227], v[24:25], off offset:3072
	v_add_u32_e32 v12, s42, v12
	v_lshl_add_u64 v[24:25], v[24:25], 0, s[12:13]
	s_waitcnt vmcnt(0)
